# v23 + K tiles also staged by LDS-DMA in the attention loop (first loop iteration keeps the register path for tiles already in flight)
# speedup vs baseline: 1.0190x; 1.0086x over previous
; #define AT_GLOAD_K(t, ks) do { const char* tb_ = (const char*)(QKV + AT_TROW(t) * QKVW) + gofs; kr[ks][0] = *(const u32x4*)(tb_); kr[ks][1] = *(const u32x4*)(tb_ + 32 * QKVW * 2); } while (0)
; #define AT_GLOAD_V(t) do { const char* tb_ = (const char*)(QKV + AT_TROW(t) * QKVW) + gofs; vr[0] = *(const u32x4*)(tb_ + 2048); vr[1] = *(const u32x4*)(tb_ + 32 * QKVW * 2 + 2048); } while (0)
; #define AT_LSTORE_K(so, ks) do { *(LAS u32x4*)(lds + (so) + koff) = kr[ks][0]; *(LAS u32x4*)(lds + (so) + koff + 4096) = kr[ks][1]; } while (0)
; #define AT_LSTORE_V(so) do { *(LAS u32x4*)(lds + (so) + voff) = vr[0]; *(LAS u32x4*)(lds + (so) + voff + 2048) = vr[1]; } while (0)
; template <bool FAST> __device__ __forceinline__ bool attn_unit(LAS unsigned char* lds, const bf16_t* QKV, bf16_t* O, int qrow0, int b, int h, int nt, float lam, float oscale, const float* subln_g) {
;     ...
;     const int lrow = tid >> 4, lch = tid & 15;
;     const unsigned gofs = (unsigned)((lrow * QKVW + 1024 + h * 128 + lch * 8) * 2);
;     const unsigned koff = (unsigned)((lch >> 3) * 8192 + lrow * 128 + (((lch & 7) ^ ((lrow >> 1) & 7)) << 4));
;     const unsigned voff = (unsigned)((lch >> 2) * 4096 + (lrow >> 3) * 512 + (lrow & 7) * 64 + (lch & 3) * 16);
;     ...
;     AT_GLOAD_K(0, 0); AT_GLOAD_V(0); AT_GLOAD_K(1, 1);
;     bf16x8 qf[4];
;     { const bf16_t* qp = QKV + (size_t)(qrow0 + wq * 32 + r32) * QKVW + h * 128 + map * 64 + hi * 8;
; #pragma unroll
;       for (int s = 0; s < 4; ++s) qf[s] = *(const bf16x8*)(qp + 16 * s); }
;     AT_LSTORE_K(0, 0); AT_LSTORE_V(32768); AT_LSTORE_K(16384, 1);
;     if constexpr (FAST) { if (2 < nt) AT_GLOAD_K(2, 0); }
;     __syncthreads();
;     f32x16 o[4], pA0, pA1, pB0, pB1;
; #pragma unroll
;     for (int c = 0; c < 4; ++c)
; #pragma unroll
;         for (int i = 0; i < 16; ++i) o[c][i] = 0.f;
; #pragma unroll
;     for (int i = 0; i < 16; ++i) { pB0[i] = 0.f; pB1[i] = 0.f; }
;     bf16x8 pf[4];
;     float mrun, lrun = 0.f;
;     int vs_prev = 32768 + 2 * 16384, vs_cur = 32768, vs_next = 32768 + 16384;
;     AT_S(pA0, pA1, 0);
;     if constexpr (FAST) mrun = 0.f; else { float tm0; AT_ROWMAX(pA0, pA1, tm0); mrun = tm0; }
;     asm volatile("s_nop 7\n\ts_nop 7" ::: "memory");
;     __syncthreads();
.LBB0_296:
	v_add_f32_e32 v15, 0, v199
	v_add_f32_e32 v0, v15, v0
	s_lshl_b32 s0, s10, 7
	v_add_f32_e32 v0, v0, v200
	s_add_i32 s0, s0, s65
	v_add_f32_e32 v237, v0, v14
	v_add_u32_e32 v0, s0, v196
	v_add_lshl_u32 v0, v0, v197, 1
	v_and_b32_e32 v236, 63, v198
	v_ashrrev_i32_e32 v211, 31, v210
	v_lshl_add_u64 v[14:15], s[74:75], 0, v[0:1]
	s_mov_b32 s0, 4
	s_mov_b32 s33, 0x10000
	s_mov_b32 s10, 0xc000
	s_mov_b32 s11, 0x8000
	s_mov_b32 s64, s56
	ds_write_b128 v227, v[10:13] offset:16384
	ds_write_b128 v227, v[184:187] offset:20480
	s_waitcnt vmcnt(2)
	ds_write_b128 v228, v[152:155] offset:49152
	s_waitcnt vmcnt(0)
	ds_write_b128 v228, v[156:159] offset:51200
	s_waitcnt lgkmcnt(0)
	s_barrier
	v_readfirstlane_b32 s100, v214
	s_movk_i32 s101, 0x1800
	v_and_b32_e32 v248, 63, v214
	v_lshrrev_b32_e32 v152, 6, v214
	v_lshrrev_b32_e32 v154, 4, v214
	v_and_b32_e32 v155, 15, v214
	v_lshrrev_b32_e32 v249, 2, v248
	v_and_b32_e32 v253, 1, v152
	v_lshl_add_u32 v249, v253, 5, v249
	v_sub_u32_e32 v249, v249, v154
	v_mul_lo_u32 v249, v249, s101
	v_lshrrev_b32_e32 v252, 1, v152
	v_and_b32_e32 v253, 3, v248
	v_lshl_add_u32 v252, v252, 2, v253
	v_sub_u32_e32 v252, v252, v155
	v_lshl_add_u32 v252, v252, 4, v249
	v_ashrrev_i32_e32 v253, 31, v252
	v_and_b32_e32 v153, 3, v152
	v_lshrrev_b32_e32 v249, 3, v248
	v_lshl_add_u32 v153, v153, 4, v249
	v_sub_u32_e32 v153, v153, v154
	v_mul_lo_u32 v156, v153, s101
	v_add_u32_e32 v158, 0xc000, v156
	v_lshrrev_b32_e32 v249, 2, v152
	v_lshlrev_b32_e32 v249, 3, v249
	v_sub_u32_e32 v249, v249, v155
	v_and_b32_e32 v153, 7, v248
	v_lshrrev_b32_e32 v154, 4, v248
	v_xor_b32_e32 v155, v153, v154
	v_add_u32_e32 v155, v155, v249
	v_lshl_add_u32 v156, v155, 4, v156
	v_add_u32_e32 v154, 4, v154
	v_xor_b32_e32 v155, v153, v154
	v_add_u32_e32 v155, v155, v249
	v_lshl_add_u32 v158, v155, 4, v158
	v_ashrrev_i32_e32 v157, 31, v156
	v_ashrrev_i32_e32 v159, 31, v158
	s_lshr_b32 s100, s100, 6
	s_lshr_b32 vcc_lo, s100, 1
	s_lshl_b32 vcc_lo, vcc_lo, 12
	s_and_b32 s101, s100, 1
	s_lshl_b32 s101, s101, 11
	s_or_b32 vcc_lo, vcc_lo, s101
	s_lshr_b32 vcc_hi, s100, 2
	s_lshl_b32 vcc_hi, vcc_hi, 13
	s_and_b32 s101, s100, 3
	s_lshl_b32 s101, s101, 11
	s_or_b32 vcc_hi, vcc_hi, s101
	s_lshl_b32 vcc_hi, vcc_hi, 16
	s_or_b32 s100, vcc_lo, vcc_hi
	s_cmpk_lt_u32 s0, 0x81
	s_cselect_b64 s[58:59], -1, 0
	s_cmpk_gt_u32 s0, 0x80
	s_cbranch_scc1 .LBB0_298

.LBB0_298:
	v_lshl_add_u64 v[152:153], v[14:15], 0, v[252:253]
	s_and_b32 s101, s100, 0xffff
	s_add_i32 m0, s33, s101
	v_add_co_u32_e32 v154, vcc, 0x18000, v152
	s_nop 1
	v_addc_co_u32_e32 v155, vcc, 0, v153, vcc
	global_load_lds_dwordx4 v[152:153], off
	s_add_i32 m0, m0, 0x400
	s_nop 0
	global_load_lds_dwordx4 v[154:155], off
	s_cmpk_gt_u32 s0, 0x81
	s_cbranch_scc1 .Lat_e_nokw
	s_cmp_eq_u32 s0, 4
	s_cbranch_scc1 .Lat_e_kreg
	s_add_i32 s101, s64, 0xffffff80
	v_mad_i64_i32 v[144:145], s[34:35], s101, v222, v[212:213]
	v_lshl_add_u64 v[146:147], v[144:145], 0, v[158:159]
	v_lshl_add_u64 v[144:145], v[144:145], 0, v[156:157]
	s_lshr_b32 s101, s100, 16
	s_mov_b32 m0, s101
	s_nop 0
	global_load_lds_dwordx4 v[144:145], off
	s_add_i32 m0, s101, 0x400
	s_nop 0
	global_load_lds_dwordx4 v[146:147], off
	s_branch .Lat_e_nokw
.Lat_e_kreg:
	ds_write_b128 v227, v[144:147]
	ds_write_b128 v227, v[148:151] offset:4096

; template <bool FAST> __device__ __forceinline__ bool attn_unit(LAS unsigned char* lds, const bf16_t* QKV, bf16_t* O, int qrow0, int b, int h, int nt, float lam, float oscale, const float* subln_g) {
;     ...
;     for (int it = 0; it < nt; it += 2) {
;         AT_STEP(it,     pA0, pA1, pB0, pB1, 16384, 0,     1, 0);
;         AT_STEP(it + 1, pB0, pB1, pA0, pA1, 0,     16384, 0, 1);
;     }
.Lat_tramp88:
	s_branch .LBB0_88
.Lat_tramp89:
	s_branch .LBB0_89

.LBB0_306:
	s_add_i32 s57, s33, 0
	s_cmpk_gt_u32 s0, 0x7f
	s_waitcnt vmcnt(0) lgkmcnt(0)
	s_barrier
	s_cbranch_scc1 .LBB0_320
	s_andn2_b64 vcc, exec, s[58:59]
	s_cbranch_vccnz .Lat_o_nokw1
	s_cmp_eq_u32 s0, 4
	s_cbranch_scc1 .Lat_o_kreg1
	s_add_i32 s101, s64, 0xffffffc0
	v_mad_i64_i32 v[10:11], s[40:41], s101, v222, v[212:213]
	v_lshl_add_u64 v[12:13], v[10:11], 0, v[158:159]
	v_lshl_add_u64 v[10:11], v[10:11], 0, v[156:157]
	s_lshr_b32 s101, s100, 16
	s_add_i32 m0, s101, 0x4000
	s_nop 0
	global_load_lds_dwordx4 v[10:11], off
	s_add_i32 m0, m0, 0x400
	s_nop 0
	global_load_lds_dwordx4 v[12:13], off
	s_branch .Lat_o_nokw1
.Lat_o_kreg1:
	ds_write_b128 v227, v[10:13] offset:16384
	ds_write_b128 v227, v[184:187] offset:20480
.Lat_o_nokw1:
	v_cndmask_b32_e64 v218, 0, 1, s[10:11]
	v_cmp_ne_u32_e64 s[40:41], 1, v218
	s_andn2_b64 vcc, exec, s[10:11]
	s_cbranch_vccz .LBB0_321

; template <bool FAST> __device__ __forceinline__ bool attn_unit(LAS unsigned char* lds, const bf16_t* QKV, bf16_t* O, int qrow0, int b, int h, int nt, float lam, float oscale, const float* subln_g) {
;     ...
;     for (int it = 0; it < nt; it += 2) {
;         AT_STEP(it,     pA0, pA1, pB0, pB1, 16384, 0,     1, 0);
;         AT_STEP(it + 1, pB0, pB1, pA0, pA1, 0,     16384, 0, 1);
;     }
.LBB0_318:
	s_add_i32 s0, s0, 2
	s_add_i32 s11, s10, 0x4000
	v_add_f32_e32 v0, v237, v0
	s_cmp_lg_u32 s10, 0x10000
	s_mov_b64 s[58:59], 0xc0000
	v_add_f32_e32 v237, v0, v128
	s_cselect_b32 s40, s11, 0x8000
	s_addk_i32 s64, 0x80
	v_lshl_add_u64 v[14:15], v[14:15], 0, s[58:59]
	s_and_b64 vcc, exec, s[34:35]
	s_waitcnt vmcnt(0) lgkmcnt(0)
	s_barrier
	s_cbranch_vccnz .LBB0_324
	s_mov_b32 s11, s33
	s_mov_b32 s33, s40
	s_cmpk_lt_u32 s0, 0x81
	s_cselect_b64 s[58:59], -1, 0
	s_cmpk_gt_u32 s0, 0x80
	s_branch .LBB0_298
.LBB0_320:
	s_andn2_b64 vcc, exec, s[58:59]
	s_cbranch_vccnz .Lat_o_nokw2
	s_cmp_eq_u32 s0, 4
	s_cbranch_scc1 .Lat_o_kreg2
	s_add_i32 s101, s64, 0xffffffc0
	v_mad_i64_i32 v[10:11], s[40:41], s101, v222, v[212:213]
	v_lshl_add_u64 v[12:13], v[10:11], 0, v[158:159]
	v_lshl_add_u64 v[10:11], v[10:11], 0, v[156:157]
	s_lshr_b32 s101, s100, 16
	s_add_i32 m0, s101, 0x4000
	s_nop 0
	global_load_lds_dwordx4 v[10:11], off
	s_add_i32 m0, m0, 0x400
	s_nop 0
	global_load_lds_dwordx4 v[12:13], off
	s_branch .Lat_o_nokw2

.LBB0_321:
	s_add_i32 s10, s64, 0xffffff80
	v_mad_i64_i32 v[152:153], s[10:11], s10, v222, v[212:213]
	v_lshl_add_u64 v[152:153], v[152:153], 0, v[252:253]
	s_add_i32 s101, s33, 0x4000
	s_cmp_lg_u32 s33, 0x10000
	s_cselect_b32 s101, s101, 0x8000
	v_add_co_u32_e32 v152, vcc, 0x800, v152
	s_and_b32 m0, s100, 0xffff
	s_add_i32 m0, m0, s101
	s_nop 0
	v_addc_co_u32_e32 v153, vcc, 0, v153, vcc
	s_nop 1
	v_add_co_u32_e32 v154, vcc, 0x18000, v152
	s_nop 1
	v_addc_co_u32_e32 v155, vcc, 0, v153, vcc
	global_load_lds_dwordx4 v[152:153], off
	s_add_i32 m0, m0, 0x400
	s_nop 0
	global_load_lds_dwordx4 v[154:155], off
	s_and_b64 vcc, exec, s[38:39]
	s_cbranch_vccz .LBB0_309
